# GEMM k-loops: LDS writes issued earlier (MFMA slots q..3q/4) behind one vmcnt, last MFMAs cover write latency before the barrier
# speedup vs baseline: 1.0226x; 1.0103x over previous
; #define G_STORE(ST, S, unused) do { char* d_ = smem + (ST) * STAGE; \
;     *(uint4*)(d_ + alo[0]) = S##a0; *(uint4*)(d_ + alo[1]) = S##a1; *(uint4*)(d_ + alo[2]) = S##a2; *(uint4*)(d_ + alo[3]) = S##a3; \
;     *(uint4*)(d_ + blo[0]) = S##b0; *(uint4*)(d_ + blo[1]) = S##b1; \
;     if (NBCH == 4) { *(uint4*)(d_ + blo[NBCH - 2]) = S##b2; *(uint4*)(d_ + blo[NBCH - 1]) = S##b3; } } while (0)
; template <int NJ, class RowA>
; DI void gemm_main(f32x16 (&acc)[2][NJ], const bf16_t* __restrict__ A, RowA rowA, size_t kstrideA, int m0, int Mmax,
;                   const bf16_t* __restrict__ Bt, size_t ldb, int n0, int nk, char* smem) {
;     ...
;   __syncthreads();
;   G_LOAD(x0, 0, 0);
;   G_LOAD(x1, 0, 1);
;   G_STORE(0, x0, 0);
;   __syncthreads();
; #pragma unroll 1
;   for (int kt = 0; kt < nk; kt += 2) {
;     G_LOAD(x0, 0, (kt + 2 < nk ? kt + 2 : nk - 1));
;     G_COMPUTE(0);
;     G_STORE(1, x1, 0);
;     __syncthreads();
;     G_LOAD(x1, 0, (kt + 3 < nk ? kt + 3 : nk - 1));
;     G_COMPUTE(1);
;     G_STORE(0, x0, 0);
;     __syncthreads();
;   }
.LBB0_12:
	s_cmp_lt_i32 s3, 12
	s_cbranch_scc0 .Lpeel_tail_12
	ds_read_b128 v[166:169], v0
	ds_read_b128 v[170:173], v139 offset:18432
	ds_read_b128 v[174:177], v139 offset:23040
	ds_read_b128 v[178:181], v0 offset:4608
	s_add_i32 s4, s3, 4
	s_min_u32 s4, s4, 15
	s_lshl_b32 s14, s4, 7
	v_lshl_add_u64 v[98:99], v[122:123], 0, s[14:15]
	v_lshl_add_u64 v[102:103], v[124:125], 0, s[14:15]
	v_lshl_add_u64 v[106:107], v[126:127], 0, s[14:15]
	v_lshl_add_u64 v[110:111], v[128:129], 0, s[14:15]
	v_lshl_add_u64 v[114:115], v[130:131], 0, s[14:15]
	v_lshl_add_u64 v[118:119], v[132:133], 0, s[14:15]
	s_add_i32 s3, s3, 2
	v_lshl_add_u64 v[158:159], v[134:135], 0, s[14:15]
	v_lshl_add_u64 v[160:161], v[136:137], 0, s[14:15]
	s_setprio 1
	ds_read_b128 v[182:185], v0 offset:32
	ds_read_b128 v[186:189], v139 offset:18464
	ds_read_b128 v[190:193], v139 offset:23072
	ds_read_b128 v[194:197], v0 offset:4640
	s_waitcnt lgkmcnt(4)
	v_mfma_f32_32x32x16_bf16 v[50:65], v[166:169], v[170:173], v[50:65]
	global_load_dwordx4 v[98:101], v[98:99], off
	v_mfma_f32_32x32x16_bf16 v[34:49], v[166:169], v[174:177], v[34:49]
	global_load_dwordx4 v[102:105], v[102:103], off
	v_mfma_f32_32x32x16_bf16 v[18:33], v[178:181], v[170:173], v[18:33]
	global_load_dwordx4 v[106:109], v[106:107], off
	v_mfma_f32_32x32x16_bf16 v[2:17], v[178:181], v[174:177], v[2:17]
	global_load_dwordx4 v[110:113], v[110:111], off
	ds_read_b128 v[166:169], v0 offset:64
	ds_read_b128 v[170:173], v139 offset:18496
	ds_read_b128 v[174:177], v139 offset:23104
	ds_read_b128 v[178:181], v0 offset:4672
	s_waitcnt lgkmcnt(4)
	v_mfma_f32_32x32x16_bf16 v[50:65], v[182:185], v[186:189], v[50:65]
	global_load_dwordx4 v[114:117], v[114:115], off
	s_waitcnt vmcnt(5)
	ds_write_b128 v138, v[78:81] offset:36864
	v_mfma_f32_32x32x16_bf16 v[34:49], v[182:185], v[190:193], v[34:49]
	global_load_dwordx4 v[118:121], v[118:119], off
	ds_write_b128 v140, v[86:89] offset:36864
	v_mfma_f32_32x32x16_bf16 v[18:33], v[194:197], v[186:189], v[18:33]
	global_load_dwordx4 v[146:149], v[160:161], off
	ds_write_b128 v142, v[90:93] offset:36864
	v_mfma_f32_32x32x16_bf16 v[2:17], v[194:197], v[190:193], v[2:17]
	global_load_dwordx4 v[150:153], v[158:159], off
	ds_write_b128 v144, v[94:97] offset:36864
	ds_read_b128 v[182:185], v0 offset:96
	ds_read_b128 v[186:189], v139 offset:18528
	ds_read_b128 v[190:193], v139 offset:23136
	ds_read_b128 v[194:197], v0 offset:4704
	s_waitcnt lgkmcnt(8)
	v_mfma_f32_32x32x16_bf16 v[50:65], v[166:169], v[170:173], v[50:65]
	ds_write_b128 v138, v[74:77] offset:55296
	v_mfma_f32_32x32x16_bf16 v[34:49], v[166:169], v[174:177], v[34:49]
	ds_write_b128 v140, v[82:85] offset:55296
	v_mfma_f32_32x32x16_bf16 v[18:33], v[178:181], v[170:173], v[18:33]
	ds_write_b128 v142, v[66:69] offset:55296
	v_mfma_f32_32x32x16_bf16 v[2:17], v[178:181], v[174:177], v[2:17]
	ds_write_b128 v144, v[70:73] offset:55296
	s_waitcnt lgkmcnt(4)
	v_mfma_f32_32x32x16_bf16 v[50:65], v[182:185], v[186:189], v[50:65]
	v_mfma_f32_32x32x16_bf16 v[34:49], v[182:185], v[190:193], v[34:49]
	v_mfma_f32_32x32x16_bf16 v[18:33], v[194:197], v[186:189], v[18:33]
	v_mfma_f32_32x32x16_bf16 v[2:17], v[194:197], v[190:193], v[2:17]
	s_setprio 0
	s_min_u32 s4, s3, 12
	s_lshl_b32 s14, s4, 7
	v_lshl_add_u64 v[66:67], v[122:123], 0, s[14:15]
	v_lshl_add_u64 v[68:69], v[124:125], 0, s[14:15]
	v_lshl_add_u64 v[70:71], v[126:127], 0, s[14:15]
	v_lshl_add_u64 v[72:73], v[128:129], 0, s[14:15]
	v_lshl_add_u64 v[74:75], v[130:131], 0, s[14:15]
	v_lshl_add_u64 v[82:83], v[132:133], 0, s[14:15]
	s_waitcnt lgkmcnt(0)
	s_barrier
	ds_read_b128 v[166:169], v0 offset:36864
	ds_read_b128 v[170:173], v139 offset:55296
	ds_read_b128 v[174:177], v139 offset:59904
	ds_read_b128 v[178:181], v0 offset:41472
	v_lshl_add_u64 v[154:155], v[134:135], 0, s[14:15]
	v_lshl_add_u64 v[156:157], v[136:137], 0, s[14:15]
	s_setprio 1
	ds_read_b128 v[182:185], v0 offset:36896
	ds_read_b128 v[186:189], v139 offset:55328
	ds_read_b128 v[190:193], v139 offset:59936
	ds_read_b128 v[194:197], v0 offset:41504
	s_waitcnt lgkmcnt(4)
	v_mfma_f32_32x32x16_bf16 v[50:65], v[166:169], v[170:173], v[50:65]
	global_load_dwordx4 v[78:81], v[66:67], off offset:384
	v_mfma_f32_32x32x16_bf16 v[34:49], v[166:169], v[174:177], v[34:49]
	global_load_dwordx4 v[86:89], v[68:69], off offset:384
	v_mfma_f32_32x32x16_bf16 v[18:33], v[178:181], v[170:173], v[18:33]
	global_load_dwordx4 v[90:93], v[70:71], off offset:384
	v_mfma_f32_32x32x16_bf16 v[2:17], v[178:181], v[174:177], v[2:17]
	global_load_dwordx4 v[94:97], v[72:73], off offset:384
	ds_read_b128 v[166:169], v0 offset:36928
	ds_read_b128 v[170:173], v139 offset:55360
	ds_read_b128 v[174:177], v139 offset:59968
	ds_read_b128 v[178:181], v0 offset:41536
	s_waitcnt lgkmcnt(4)
	v_mfma_f32_32x32x16_bf16 v[50:65], v[182:185], v[186:189], v[50:65]
	global_load_dwordx4 v[74:77], v[74:75], off offset:384
	s_waitcnt vmcnt(5)
	ds_write_b128 v138, v[98:101]
	v_mfma_f32_32x32x16_bf16 v[34:49], v[182:185], v[190:193], v[34:49]
	global_load_dwordx4 v[82:85], v[82:83], off offset:384
	ds_write_b128 v140, v[102:105]
	v_mfma_f32_32x32x16_bf16 v[18:33], v[194:197], v[186:189], v[18:33]
	global_load_dwordx4 v[66:69], v[154:155], off offset:384
	ds_write_b128 v142, v[106:109]
	v_mfma_f32_32x32x16_bf16 v[2:17], v[194:197], v[190:193], v[2:17]
	global_load_dwordx4 v[70:73], v[156:157], off offset:384
	ds_write_b128 v144, v[110:113]
	ds_read_b128 v[182:185], v0 offset:36960
	ds_read_b128 v[186:189], v139 offset:55392
	ds_read_b128 v[190:193], v139 offset:60000
	ds_read_b128 v[194:197], v0 offset:41568
	s_waitcnt lgkmcnt(8)
	v_mfma_f32_32x32x16_bf16 v[50:65], v[166:169], v[170:173], v[50:65]
	ds_write_b128 v138, v[114:117] offset:18432
	v_mfma_f32_32x32x16_bf16 v[34:49], v[166:169], v[174:177], v[34:49]
	ds_write_b128 v140, v[118:121] offset:18432
	v_mfma_f32_32x32x16_bf16 v[18:33], v[178:181], v[170:173], v[18:33]
	ds_write_b128 v142, v[150:153] offset:18432
	v_mfma_f32_32x32x16_bf16 v[2:17], v[178:181], v[174:177], v[2:17]
	ds_write_b128 v144, v[146:149] offset:18432
	s_waitcnt lgkmcnt(4)
	v_mfma_f32_32x32x16_bf16 v[50:65], v[182:185], v[186:189], v[50:65]
	v_mfma_f32_32x32x16_bf16 v[34:49], v[182:185], v[190:193], v[34:49]
	v_mfma_f32_32x32x16_bf16 v[18:33], v[194:197], v[186:189], v[18:33]
	v_mfma_f32_32x32x16_bf16 v[2:17], v[194:197], v[190:193], v[2:17]
	s_setprio 0
	s_cmp_lt_u32 s3, 14
	s_waitcnt lgkmcnt(0)
	s_barrier
	s_branch .LBB0_12

; #define G_STORE(ST, S, unused) do { char* d_ = smem + (ST) * STAGE; \
;     *(uint4*)(d_ + alo[0]) = S##a0; *(uint4*)(d_ + alo[1]) = S##a1; *(uint4*)(d_ + alo[2]) = S##a2; *(uint4*)(d_ + alo[3]) = S##a3; \
;     *(uint4*)(d_ + blo[0]) = S##b0; *(uint4*)(d_ + blo[1]) = S##b1; \
;     if (NBCH == 4) { *(uint4*)(d_ + blo[NBCH - 2]) = S##b2; *(uint4*)(d_ + blo[NBCH - 1]) = S##b3; } } while (0)
; template <int NJ, class RowA>
; DI void gemm_main(f32x16 (&acc)[2][NJ], const bf16_t* __restrict__ A, RowA rowA, size_t kstrideA, int m0, int Mmax,
;                   const bf16_t* __restrict__ Bt, size_t ldb, int n0, int nk, char* smem) {
;     ...
;   __syncthreads();
;   G_LOAD(x0, 0, 0);
;   G_LOAD(x1, 0, 1);
;   G_STORE(0, x0, 0);
;   __syncthreads();
; #pragma unroll 1
;   for (int kt = 0; kt < nk; kt += 2) {
;     G_LOAD(x0, 0, (kt + 2 < nk ? kt + 2 : nk - 1));
;     G_COMPUTE(0);
;     G_STORE(1, x1, 0);
;     __syncthreads();
;     G_LOAD(x1, 0, (kt + 3 < nk ? kt + 3 : nk - 1));
;     G_COMPUTE(1);
;     G_STORE(0, x0, 0);
;     __syncthreads();
;   }
.LBB0_19:
	s_cmp_lt_i32 s4, 12
	s_cbranch_scc0 .Lpeel_tail_19
	ds_read_b128 v[176:179], v0
	ds_read_b128 v[180:183], v71 offset:18432
	ds_read_b128 v[184:187], v0 offset:4608
	s_add_i32 s5, s4, 4
	s_min_u32 s5, s5, 15
	s_lshl_b32 s14, s5, 7
	v_lshl_add_u64 v[78:79], v[58:59], 0, s[14:15]
	v_lshl_add_u64 v[82:83], v[60:61], 0, s[14:15]
	v_lshl_add_u64 v[86:87], v[62:63], 0, s[14:15]
	v_lshl_add_u64 v[122:123], v[64:65], 0, s[14:15]
	v_lshl_add_u64 v[126:127], v[66:67], 0, s[14:15]
	v_lshl_add_u64 v[130:131], v[68:69], 0, s[14:15]
	s_add_i32 s4, s4, 2
	s_setprio 1
	ds_read_b128 v[188:191], v0 offset:32
	ds_read_b128 v[192:195], v71 offset:18464
	ds_read_b128 v[196:199], v0 offset:4640
	s_waitcnt lgkmcnt(3)
	v_mfma_f32_32x32x16_bf16 v[18:33], v[176:179], v[180:183], v[18:33]
	global_load_dwordx4 v[78:81], v[78:79], off
	s_nop 0
	global_load_dwordx4 v[82:85], v[82:83], off
	v_mfma_f32_32x32x16_bf16 v[2:17], v[184:187], v[180:183], v[2:17]
	global_load_dwordx4 v[86:89], v[86:87], off
	ds_read_b128 v[176:179], v0 offset:64
	ds_read_b128 v[180:183], v71 offset:18496
	ds_read_b128 v[184:187], v0 offset:4672
	s_waitcnt lgkmcnt(3)
	v_mfma_f32_32x32x16_bf16 v[18:33], v[188:191], v[192:195], v[18:33]
	global_load_dwordx4 v[122:125], v[122:123], off
	s_nop 0
	global_load_dwordx4 v[126:129], v[126:127], off
	s_waitcnt vmcnt(5)
	ds_write_b128 v70, v[34:37] offset:27648
	ds_write_b128 v72, v[38:41] offset:27648
	v_mfma_f32_32x32x16_bf16 v[2:17], v[196:199], v[192:195], v[2:17]
	global_load_dwordx4 v[130:133], v[130:131], off
	ds_write_b128 v74, v[42:45] offset:27648
	ds_read_b128 v[188:191], v0 offset:96
	ds_read_b128 v[192:195], v71 offset:18528
	ds_read_b128 v[196:199], v0 offset:4704
	s_waitcnt lgkmcnt(6)
	v_mfma_f32_32x32x16_bf16 v[18:33], v[176:179], v[180:183], v[18:33]
	ds_write_b128 v76, v[54:57] offset:27648
	ds_write_b128 v70, v[46:49] offset:46080
	v_mfma_f32_32x32x16_bf16 v[2:17], v[184:187], v[180:183], v[2:17]
	ds_write_b128 v72, v[50:53] offset:46080
	s_waitcnt lgkmcnt(3)
	v_mfma_f32_32x32x16_bf16 v[18:33], v[188:191], v[192:195], v[18:33]
	v_mfma_f32_32x32x16_bf16 v[2:17], v[196:199], v[192:195], v[2:17]
	s_setprio 0
	s_min_u32 s5, s4, 12
	s_lshl_b32 s14, s5, 7
	v_lshl_add_u64 v[34:35], v[58:59], 0, s[14:15]
	v_lshl_add_u64 v[38:39], v[60:61], 0, s[14:15]
	v_lshl_add_u64 v[42:43], v[62:63], 0, s[14:15]
	v_lshl_add_u64 v[46:47], v[64:65], 0, s[14:15]
	v_lshl_add_u64 v[48:49], v[66:67], 0, s[14:15]
	v_lshl_add_u64 v[50:51], v[68:69], 0, s[14:15]
	s_waitcnt lgkmcnt(0)
	s_barrier
	ds_read_b128 v[176:179], v0 offset:27648
	ds_read_b128 v[180:183], v71 offset:46080
	ds_read_b128 v[184:187], v0 offset:32256
	s_setprio 1
	ds_read_b128 v[188:191], v0 offset:27680
	ds_read_b128 v[192:195], v71 offset:46112
	ds_read_b128 v[196:199], v0 offset:32288
	s_waitcnt lgkmcnt(3)
	v_mfma_f32_32x32x16_bf16 v[18:33], v[176:179], v[180:183], v[18:33]
	global_load_dwordx4 v[34:37], v[34:35], off offset:384
	s_nop 0
	global_load_dwordx4 v[38:41], v[38:39], off offset:384
	v_mfma_f32_32x32x16_bf16 v[2:17], v[184:187], v[180:183], v[2:17]
	global_load_dwordx4 v[42:45], v[42:43], off offset:384
	ds_read_b128 v[176:179], v0 offset:27712
	ds_read_b128 v[180:183], v71 offset:46144
	ds_read_b128 v[184:187], v0 offset:32320
	s_waitcnt lgkmcnt(3)
	v_mfma_f32_32x32x16_bf16 v[18:33], v[188:191], v[192:195], v[18:33]
	global_load_dwordx4 v[54:57], v[46:47], off offset:384
	s_nop 0
	global_load_dwordx4 v[46:49], v[48:49], off offset:384
	s_waitcnt vmcnt(5)
	ds_write_b128 v70, v[78:81]
	ds_write_b128 v72, v[82:85]
	v_mfma_f32_32x32x16_bf16 v[2:17], v[196:199], v[192:195], v[2:17]
	global_load_dwordx4 v[50:53], v[50:51], off offset:384
	ds_write_b128 v74, v[86:89]
	ds_read_b128 v[188:191], v0 offset:27744
	ds_read_b128 v[192:195], v71 offset:46176
	ds_read_b128 v[196:199], v0 offset:32352
	s_waitcnt lgkmcnt(6)
	v_mfma_f32_32x32x16_bf16 v[18:33], v[176:179], v[180:183], v[18:33]
	ds_write_b128 v76, v[122:125]
	ds_write_b128 v70, v[126:129] offset:18432
	v_mfma_f32_32x32x16_bf16 v[2:17], v[184:187], v[180:183], v[2:17]
	ds_write_b128 v72, v[130:133] offset:18432
	s_waitcnt lgkmcnt(3)
	v_mfma_f32_32x32x16_bf16 v[18:33], v[188:191], v[192:195], v[18:33]
	v_mfma_f32_32x32x16_bf16 v[2:17], v[196:199], v[192:195], v[2:17]
	s_setprio 0
	s_cmp_lt_u32 s4, 14
	s_waitcnt lgkmcnt(0)
	s_barrier
	s_branch .LBB0_19

; #define G_STORE(ST, S, unused) do { char* d_ = smem + (ST) * STAGE; \
;     *(uint4*)(d_ + alo[0]) = S##a0; *(uint4*)(d_ + alo[1]) = S##a1; *(uint4*)(d_ + alo[2]) = S##a2; *(uint4*)(d_ + alo[3]) = S##a3; \
;     *(uint4*)(d_ + blo[0]) = S##b0; *(uint4*)(d_ + blo[1]) = S##b1; \
;     if (NBCH == 4) { *(uint4*)(d_ + blo[NBCH - 2]) = S##b2; *(uint4*)(d_ + blo[NBCH - 1]) = S##b3; } } while (0)
; template <int NJ, class RowA>
; DI void gemm_main(f32x16 (&acc)[2][NJ], const bf16_t* __restrict__ A, RowA rowA, size_t kstrideA, int m0, int Mmax,
;                   const bf16_t* __restrict__ Bt, size_t ldb, int n0, int nk, char* smem) {
;     ...
;   __syncthreads();
;   G_LOAD(x0, 0, 0);
;   G_LOAD(x1, 0, 1);
;   G_STORE(0, x0, 0);
;   __syncthreads();
; #pragma unroll 1
;   for (int kt = 0; kt < nk; kt += 2) {
;     G_LOAD(x0, 0, (kt + 2 < nk ? kt + 2 : nk - 1));
;     G_COMPUTE(0);
;     G_STORE(1, x1, 0);
;     __syncthreads();
;     G_LOAD(x1, 0, (kt + 3 < nk ? kt + 3 : nk - 1));
;     G_COMPUTE(1);
;     G_STORE(0, x0, 0);
;     __syncthreads();
;   }
.LBB0_21:
	s_add_i32 s7, s5, -1
	s_cmp_lt_u32 s7, s4
	s_cbranch_scc0 .Lpeel_tail_21
	ds_read_b128 v[176:179], v0
	ds_read_b128 v[180:183], v135 offset:18432
	ds_read_b128 v[184:187], v0 offset:4608
	s_add_i32 s7, s5, -1
	s_min_u32 s14, s7, s6
	s_lshl_b64 s[8:9], s[14:15], 7
	v_lshl_add_u64 v[144:145], v[122:123], 0, s[8:9]
	v_lshl_add_u64 v[148:149], v[124:125], 0, s[8:9]
	v_lshl_add_u64 v[152:153], v[126:127], 0, s[8:9]
	v_lshl_add_u64 v[156:157], v[128:129], 0, s[8:9]
	v_lshl_add_u64 v[160:161], v[130:131], 0, s[8:9]
	v_lshl_add_u64 v[164:165], v[132:133], 0, s[8:9]
	s_setprio 1
	ds_read_b128 v[188:191], v0 offset:32
	ds_read_b128 v[192:195], v135 offset:18464
	ds_read_b128 v[196:199], v0 offset:4640
	s_waitcnt lgkmcnt(3)
	v_mfma_f32_32x32x16_bf16 v[50:65], v[176:179], v[180:183], v[50:65]
	global_load_dwordx4 v[144:147], v[144:145], off
	s_nop 0
	global_load_dwordx4 v[148:151], v[148:149], off
	v_mfma_f32_32x32x16_bf16 v[34:49], v[184:187], v[180:183], v[34:49]
	global_load_dwordx4 v[152:155], v[152:153], off
	ds_read_b128 v[176:179], v0 offset:64
	ds_read_b128 v[180:183], v135 offset:18496
	ds_read_b128 v[184:187], v0 offset:4672
	s_waitcnt lgkmcnt(3)
	v_mfma_f32_32x32x16_bf16 v[50:65], v[188:191], v[192:195], v[50:65]
	global_load_dwordx4 v[156:159], v[156:157], off
	s_nop 0
	global_load_dwordx4 v[160:163], v[160:161], off
	s_waitcnt vmcnt(5)
	ds_write_b128 v134, v[66:69] offset:27648
	ds_write_b128 v136, v[70:73] offset:27648
	v_mfma_f32_32x32x16_bf16 v[34:49], v[196:199], v[192:195], v[34:49]
	global_load_dwordx4 v[164:167], v[164:165], off
	ds_write_b128 v138, v[74:77] offset:27648
	ds_read_b128 v[188:191], v0 offset:96
	ds_read_b128 v[192:195], v135 offset:18528
	ds_read_b128 v[196:199], v0 offset:4704
	s_waitcnt lgkmcnt(6)
	v_mfma_f32_32x32x16_bf16 v[50:65], v[176:179], v[180:183], v[50:65]
	ds_write_b128 v140, v[78:81] offset:27648
	ds_write_b128 v134, v[82:85] offset:46080
	v_mfma_f32_32x32x16_bf16 v[34:49], v[184:187], v[180:183], v[34:49]
	ds_write_b128 v136, v[86:89] offset:46080
	s_waitcnt lgkmcnt(3)
	v_mfma_f32_32x32x16_bf16 v[50:65], v[188:191], v[192:195], v[50:65]
	v_mfma_f32_32x32x16_bf16 v[34:49], v[196:199], v[192:195], v[34:49]
	s_setprio 0
	s_min_u32 s14, s5, s6
	s_lshl_b64 s[8:9], s[14:15], 7
	v_lshl_add_u64 v[66:67], v[122:123], 0, s[8:9]
	v_lshl_add_u64 v[70:71], v[124:125], 0, s[8:9]
	v_lshl_add_u64 v[74:75], v[126:127], 0, s[8:9]
	v_lshl_add_u64 v[78:79], v[128:129], 0, s[8:9]
	v_lshl_add_u64 v[82:83], v[130:131], 0, s[8:9]
	v_lshl_add_u64 v[86:87], v[132:133], 0, s[8:9]
	s_waitcnt lgkmcnt(0)
	s_barrier
	ds_read_b128 v[176:179], v0 offset:27648
	ds_read_b128 v[180:183], v135 offset:46080
	ds_read_b128 v[184:187], v0 offset:32256
	s_setprio 1
	ds_read_b128 v[188:191], v0 offset:27680
	ds_read_b128 v[192:195], v135 offset:46112
	ds_read_b128 v[196:199], v0 offset:32288
	s_waitcnt lgkmcnt(3)
	v_mfma_f32_32x32x16_bf16 v[50:65], v[176:179], v[180:183], v[50:65]
	global_load_dwordx4 v[66:69], v[66:67], off
	s_nop 0
	global_load_dwordx4 v[70:73], v[70:71], off
	v_mfma_f32_32x32x16_bf16 v[34:49], v[184:187], v[180:183], v[34:49]
	global_load_dwordx4 v[74:77], v[74:75], off
	ds_read_b128 v[176:179], v0 offset:27712
	ds_read_b128 v[180:183], v135 offset:46144
	ds_read_b128 v[184:187], v0 offset:32320
	s_waitcnt lgkmcnt(3)
	v_mfma_f32_32x32x16_bf16 v[50:65], v[188:191], v[192:195], v[50:65]
	global_load_dwordx4 v[78:81], v[78:79], off
	s_nop 0
	global_load_dwordx4 v[82:85], v[82:83], off
	s_waitcnt vmcnt(5)
	ds_write_b128 v134, v[144:147]
	ds_write_b128 v136, v[148:151]
	v_mfma_f32_32x32x16_bf16 v[34:49], v[196:199], v[192:195], v[34:49]
	global_load_dwordx4 v[86:89], v[86:87], off
	ds_write_b128 v138, v[152:155]
	ds_read_b128 v[188:191], v0 offset:27744
	ds_read_b128 v[192:195], v135 offset:46176
	ds_read_b128 v[196:199], v0 offset:32352
	s_waitcnt lgkmcnt(6)
	v_mfma_f32_32x32x16_bf16 v[50:65], v[176:179], v[180:183], v[50:65]
	ds_write_b128 v140, v[156:159]
	ds_write_b128 v134, v[160:163] offset:18432
	v_mfma_f32_32x32x16_bf16 v[34:49], v[184:187], v[180:183], v[34:49]
	ds_write_b128 v136, v[164:167] offset:18432
	s_waitcnt lgkmcnt(3)
	v_mfma_f32_32x32x16_bf16 v[50:65], v[188:191], v[192:195], v[50:65]
	v_mfma_f32_32x32x16_bf16 v[34:49], v[196:199], v[192:195], v[34:49]
	s_setprio 0
	s_add_i32 s5, s5, 2
	s_cmp_lt_u32 s7, s4
	s_waitcnt lgkmcnt(0)
	s_barrier
	s_branch .LBB0_21

; #define G_STORE(ST, S, unused) do { char* d_ = smem + (ST) * STAGE; \
;     *(uint4*)(d_ + alo[0]) = S##a0; *(uint4*)(d_ + alo[1]) = S##a1; *(uint4*)(d_ + alo[2]) = S##a2; *(uint4*)(d_ + alo[3]) = S##a3; \
;     *(uint4*)(d_ + blo[0]) = S##b0; *(uint4*)(d_ + blo[1]) = S##b1; \
;     if (NBCH == 4) { *(uint4*)(d_ + blo[NBCH - 2]) = S##b2; *(uint4*)(d_ + blo[NBCH - 1]) = S##b3; } } while (0)
; template <int NJ, class RowA>
; DI void gemm_main(f32x16 (&acc)[2][NJ], const bf16_t* __restrict__ A, RowA rowA, size_t kstrideA, int m0, int Mmax,
;                   const bf16_t* __restrict__ Bt, size_t ldb, int n0, int nk, char* smem) {
;     ...
;   __syncthreads();
;   G_LOAD(x0, 0, 0);
;   G_LOAD(x1, 0, 1);
;   G_STORE(0, x0, 0);
;   __syncthreads();
; #pragma unroll 1
;   for (int kt = 0; kt < nk; kt += 2) {
;     G_LOAD(x0, 0, (kt + 2 < nk ? kt + 2 : nk - 1));
;     G_COMPUTE(0);
;     G_STORE(1, x1, 0);
;     __syncthreads();
;     G_LOAD(x1, 0, (kt + 3 < nk ? kt + 3 : nk - 1));
;     G_COMPUTE(1);
;     G_STORE(0, x0, 0);
;     __syncthreads();
;   }
.LBB0_1956:
	s_cmp_lt_i32 s0, 12
	s_cbranch_scc0 .Lpeel_tail_1956
	ds_read_b128 v[166:169], v0
	ds_read_b128 v[170:173], v139 offset:18432
	ds_read_b128 v[174:177], v139 offset:23040
	ds_read_b128 v[178:181], v0 offset:4608
	s_add_i32 s1, s0, 4
	s_min_u32 s1, s1, 15
	s_lshl_b32 s14, s1, 7
	v_lshl_add_u64 v[98:99], v[122:123], 0, s[14:15]
	v_lshl_add_u64 v[102:103], v[124:125], 0, s[14:15]
	v_lshl_add_u64 v[106:107], v[126:127], 0, s[14:15]
	v_lshl_add_u64 v[110:111], v[128:129], 0, s[14:15]
	v_lshl_add_u64 v[114:115], v[130:131], 0, s[14:15]
	v_lshl_add_u64 v[118:119], v[132:133], 0, s[14:15]
	s_add_i32 s0, s0, 2
	v_lshl_add_u64 v[158:159], v[134:135], 0, s[14:15]
	v_lshl_add_u64 v[160:161], v[136:137], 0, s[14:15]
	s_setprio 1
	ds_read_b128 v[182:185], v0 offset:32
	ds_read_b128 v[186:189], v139 offset:18464
	ds_read_b128 v[190:193], v139 offset:23072
	ds_read_b128 v[194:197], v0 offset:4640
	s_waitcnt lgkmcnt(4)
	v_mfma_f32_32x32x16_bf16 v[50:65], v[166:169], v[170:173], v[50:65]
	global_load_dwordx4 v[98:101], v[98:99], off
	v_mfma_f32_32x32x16_bf16 v[34:49], v[166:169], v[174:177], v[34:49]
	global_load_dwordx4 v[102:105], v[102:103], off
	v_mfma_f32_32x32x16_bf16 v[18:33], v[178:181], v[170:173], v[18:33]
	global_load_dwordx4 v[106:109], v[106:107], off
	v_mfma_f32_32x32x16_bf16 v[2:17], v[178:181], v[174:177], v[2:17]
	global_load_dwordx4 v[110:113], v[110:111], off
	ds_read_b128 v[166:169], v0 offset:64
	ds_read_b128 v[170:173], v139 offset:18496
	ds_read_b128 v[174:177], v139 offset:23104
	ds_read_b128 v[178:181], v0 offset:4672
	s_waitcnt lgkmcnt(4)
	v_mfma_f32_32x32x16_bf16 v[50:65], v[182:185], v[186:189], v[50:65]
	global_load_dwordx4 v[114:117], v[114:115], off
	s_waitcnt vmcnt(5)
	ds_write_b128 v138, v[74:77] offset:36864
	v_mfma_f32_32x32x16_bf16 v[34:49], v[182:185], v[190:193], v[34:49]
	global_load_dwordx4 v[118:121], v[118:119], off
	ds_write_b128 v140, v[78:81] offset:36864
	v_mfma_f32_32x32x16_bf16 v[18:33], v[194:197], v[186:189], v[18:33]
	global_load_dwordx4 v[146:149], v[160:161], off
	ds_write_b128 v142, v[82:85] offset:36864
	v_mfma_f32_32x32x16_bf16 v[2:17], v[194:197], v[190:193], v[2:17]
	global_load_dwordx4 v[150:153], v[158:159], off
	ds_write_b128 v144, v[86:89] offset:36864
	ds_read_b128 v[182:185], v0 offset:96
	ds_read_b128 v[186:189], v139 offset:18528
	ds_read_b128 v[190:193], v139 offset:23136
	ds_read_b128 v[194:197], v0 offset:4704
	s_waitcnt lgkmcnt(8)
	v_mfma_f32_32x32x16_bf16 v[50:65], v[166:169], v[170:173], v[50:65]
	ds_write_b128 v138, v[90:93] offset:55296
	v_mfma_f32_32x32x16_bf16 v[34:49], v[166:169], v[174:177], v[34:49]
	ds_write_b128 v140, v[94:97] offset:55296
	v_mfma_f32_32x32x16_bf16 v[18:33], v[178:181], v[170:173], v[18:33]
	ds_write_b128 v142, v[66:69] offset:55296
	v_mfma_f32_32x32x16_bf16 v[2:17], v[178:181], v[174:177], v[2:17]
	ds_write_b128 v144, v[70:73] offset:55296
	s_waitcnt lgkmcnt(4)
	v_mfma_f32_32x32x16_bf16 v[50:65], v[182:185], v[186:189], v[50:65]
	v_mfma_f32_32x32x16_bf16 v[34:49], v[182:185], v[190:193], v[34:49]
	v_mfma_f32_32x32x16_bf16 v[18:33], v[194:197], v[186:189], v[18:33]
	v_mfma_f32_32x32x16_bf16 v[2:17], v[194:197], v[190:193], v[2:17]
	s_setprio 0
	s_min_u32 s1, s0, 12
	s_lshl_b32 s14, s1, 7
	v_lshl_add_u64 v[66:67], v[122:123], 0, s[14:15]
	v_lshl_add_u64 v[68:69], v[124:125], 0, s[14:15]
	v_lshl_add_u64 v[70:71], v[126:127], 0, s[14:15]
	v_lshl_add_u64 v[72:73], v[128:129], 0, s[14:15]
	v_lshl_add_u64 v[90:91], v[130:131], 0, s[14:15]
	v_lshl_add_u64 v[94:95], v[132:133], 0, s[14:15]
	s_waitcnt lgkmcnt(0)
	s_barrier
	ds_read_b128 v[166:169], v0 offset:36864
	ds_read_b128 v[170:173], v139 offset:55296
	ds_read_b128 v[174:177], v139 offset:59904
	ds_read_b128 v[178:181], v0 offset:41472
	v_lshl_add_u64 v[154:155], v[134:135], 0, s[14:15]
	v_lshl_add_u64 v[156:157], v[136:137], 0, s[14:15]
	s_setprio 1
	ds_read_b128 v[182:185], v0 offset:36896
	ds_read_b128 v[186:189], v139 offset:55328
	ds_read_b128 v[190:193], v139 offset:59936
	ds_read_b128 v[194:197], v0 offset:41504
	s_waitcnt lgkmcnt(4)
	v_mfma_f32_32x32x16_bf16 v[50:65], v[166:169], v[170:173], v[50:65]
	global_load_dwordx4 v[74:77], v[66:67], off offset:384
	v_mfma_f32_32x32x16_bf16 v[34:49], v[166:169], v[174:177], v[34:49]
	global_load_dwordx4 v[78:81], v[68:69], off offset:384
	v_mfma_f32_32x32x16_bf16 v[18:33], v[178:181], v[170:173], v[18:33]
	global_load_dwordx4 v[82:85], v[70:71], off offset:384
	v_mfma_f32_32x32x16_bf16 v[2:17], v[178:181], v[174:177], v[2:17]
	global_load_dwordx4 v[86:89], v[72:73], off offset:384
	ds_read_b128 v[166:169], v0 offset:36928
	ds_read_b128 v[170:173], v139 offset:55360
	ds_read_b128 v[174:177], v139 offset:59968
	ds_read_b128 v[178:181], v0 offset:41536
	s_waitcnt lgkmcnt(4)
	v_mfma_f32_32x32x16_bf16 v[50:65], v[182:185], v[186:189], v[50:65]
	global_load_dwordx4 v[90:93], v[90:91], off offset:384
	s_waitcnt vmcnt(5)
	ds_write_b128 v138, v[98:101]
	v_mfma_f32_32x32x16_bf16 v[34:49], v[182:185], v[190:193], v[34:49]
	global_load_dwordx4 v[94:97], v[94:95], off offset:384
	ds_write_b128 v140, v[102:105]
	v_mfma_f32_32x32x16_bf16 v[18:33], v[194:197], v[186:189], v[18:33]
	global_load_dwordx4 v[66:69], v[154:155], off offset:384
	ds_write_b128 v142, v[106:109]
	v_mfma_f32_32x32x16_bf16 v[2:17], v[194:197], v[190:193], v[2:17]
	global_load_dwordx4 v[70:73], v[156:157], off offset:384
	ds_write_b128 v144, v[110:113]
	ds_read_b128 v[182:185], v0 offset:36960
	ds_read_b128 v[186:189], v139 offset:55392
	ds_read_b128 v[190:193], v139 offset:60000
	ds_read_b128 v[194:197], v0 offset:41568
	s_waitcnt lgkmcnt(8)
	v_mfma_f32_32x32x16_bf16 v[50:65], v[166:169], v[170:173], v[50:65]
	ds_write_b128 v138, v[114:117] offset:18432
	v_mfma_f32_32x32x16_bf16 v[34:49], v[166:169], v[174:177], v[34:49]
	ds_write_b128 v140, v[118:121] offset:18432
	v_mfma_f32_32x32x16_bf16 v[18:33], v[178:181], v[170:173], v[18:33]
	ds_write_b128 v142, v[150:153] offset:18432
	v_mfma_f32_32x32x16_bf16 v[2:17], v[178:181], v[174:177], v[2:17]
	ds_write_b128 v144, v[146:149] offset:18432
	s_waitcnt lgkmcnt(4)
	v_mfma_f32_32x32x16_bf16 v[50:65], v[182:185], v[186:189], v[50:65]
	v_mfma_f32_32x32x16_bf16 v[34:49], v[182:185], v[190:193], v[34:49]
	v_mfma_f32_32x32x16_bf16 v[18:33], v[194:197], v[186:189], v[18:33]
	v_mfma_f32_32x32x16_bf16 v[2:17], v[194:197], v[190:193], v[2:17]
	s_setprio 0
	s_cmp_lt_u32 s0, 14
	s_waitcnt lgkmcnt(0)
	s_barrier
	s_branch .LBB0_1956
